# SEL attention loop restructured: both QK MFMA groups first (second score tile in spare VGPRs), K prefetch right after, V prefetch for the next tile at loop end
# speedup vs baseline: 1.0032x; 1.0032x over previous
.LBB0_625:
	v_mov_b32_e32 v0, 0x1400000
	s_add_i32 s82, s18, s16
	v_mad_i64_i32 v[2:3], s[4:5], s16, v0, v[154:155]
	s_ashr_i32 s83, s82, 31
	s_lshl_b32 s74, s24, 7
	s_lshl_b64 s[4:5], s[82:83], 19
	s_waitcnt lgkmcnt(0)
	v_lshl_add_u64 v[148:149], v[2:3], 0, s[74:75]
	v_lshl_add_u64 v[2:3], v[164:165], 0, s[4:5]
	s_lshl_b64 s[4:5], 2, s17
	ds_read_b64 v[152:153], v37 offset:18432
	s_waitcnt lgkmcnt(0)
	s_add_u32 s4, s4, -1
	v_and_b32_e32 v8, 31, v195
	v_ashrrev_i32_e32 v9, 5, v195
	s_addc_u32 s5, s5, -1
	v_mul_u32_u24_e32 v0, 0xa00, v8
	v_lshlrev_b32_e32 v6, 3, v9
	s_and_b64 s[94:95], s[20:21], s[4:5]
	v_lshlrev_b32_e32 v0, 1, v0
	v_ashrrev_i32_e32 v7, 31, v6
	v_lshl_add_u64 v[4:5], v[148:149], 0, v[0:1]
	v_lshlrev_b64 v[6:7], 1, v[6:7]
	s_ff1_i32_b64 s4, s[94:95]
	v_lshl_add_u64 v[180:181], v[4:5], 0, v[6:7]
	v_lshl_add_u64 v[2:3], v[2:3], 0, v[6:7]
	v_lshlrev_b32_e32 v0, 5, v8
	v_mov_b32_e32 v14, v1
	v_mov_b32_e32 v15, v1
	v_lshl_add_u64 v[182:183], v[2:3], 0, v[0:1]
	s_mov_b64 s[100:101], 0x1400000
	s_mov_b32 s99, 0
	v_lshl_add_u64 v[240:241], v[182:183], 0, s[100:101]
	s_lshl_b32 s74, s4, 13
	v_lshl_add_u64 v[4:5], v[240:241], 0, s[74:75]
	global_load_dwordx4 v[118:121], v[4:5], off
	global_load_dwordx4 v[122:125], v[4:5], off offset:1024
	global_load_dwordx4 v[126:129], v[4:5], off offset:2048
	global_load_dwordx4 v[114:117], v[4:5], off offset:3072
	v_lshlrev_b32_e32 v173, 2, v9
	v_mov_b32_e32 v0, v1
	v_mov_b32_e32 v2, v1
	v_mov_b32_e32 v3, v1
	v_mov_b32_e32 v4, v1
	v_mov_b32_e32 v5, v1
	v_mov_b32_e32 v6, v1
	v_mov_b32_e32 v7, v1
	v_mov_b32_e32 v8, v1
	v_mov_b32_e32 v9, v1
	v_mov_b32_e32 v10, v1
	v_mov_b32_e32 v11, v1
	v_mov_b32_e32 v12, v1
	v_mov_b32_e32 v13, v1
	v_mov_b64_e32 v[64:65], v[14:15]
	v_mov_b64_e32 v[48:49], v[14:15]
	v_mov_b64_e32 v[32:33], v[14:15]
	v_mov_b32_e32 v151, 0
	v_mov_b64_e32 v[62:63], v[12:13]
	v_mov_b64_e32 v[60:61], v[10:11]
	v_mov_b64_e32 v[58:59], v[8:9]
	v_mov_b64_e32 v[56:57], v[6:7]
	v_mov_b64_e32 v[54:55], v[4:5]
	v_mov_b64_e32 v[52:53], v[2:3]
	v_mov_b64_e32 v[50:51], v[0:1]
	v_mov_b64_e32 v[46:47], v[12:13]
	v_mov_b64_e32 v[44:45], v[10:11]
	v_mov_b64_e32 v[42:43], v[8:9]
	v_mov_b64_e32 v[40:41], v[6:7]
	v_mov_b64_e32 v[38:39], v[4:5]
	v_mov_b64_e32 v[36:37], v[2:3]
	v_mov_b64_e32 v[34:35], v[0:1]
	v_mov_b64_e32 v[30:31], v[12:13]
	v_mov_b64_e32 v[28:29], v[10:11]
	v_mov_b64_e32 v[26:27], v[8:9]
	v_mov_b64_e32 v[24:25], v[6:7]
	v_mov_b64_e32 v[22:23], v[4:5]
	v_mov_b64_e32 v[20:21], v[2:3]
	v_mov_b64_e32 v[18:19], v[0:1]
	v_mov_b64_e32 v[16:17], v[14:15]
	v_add_u32_e32 v175, 6, v172
	v_add_u32_e32 v184, 5, v172
	s_mov_b32 s8, 0
	v_mov_b32_e32 v203, 0xf149f2ca
	v_mov_b32_e32 v150, v151
	v_mov_b32_e32 v185, 0xf149f2ca
	v_mov_b64_e32 v[14:15], v[12:13]
	v_mov_b64_e32 v[12:13], v[10:11]
	v_mov_b64_e32 v[10:11], v[8:9]
	v_mov_b64_e32 v[8:9], v[6:7]
	v_mov_b64_e32 v[6:7], v[4:5]
	v_mov_b64_e32 v[4:5], v[2:3]
	v_mov_b64_e32 v[2:3], v[0:1]
	s_mov_b32 s83, s4
	s_lshl_b32 s74, s4, 13
	v_lshl_add_u64 v[220:221], v[182:183], 0, s[74:75]
	global_load_dwordx4 v[142:145], v[220:221], off
	global_load_dwordx4 v[138:141], v[220:221], off offset:2048
	global_load_dwordx4 v[134:137], v[220:221], off offset:1024
	global_load_dwordx4 v[130:133], v[220:221], off offset:3072

.LBB0_630:
	s_waitcnt vmcnt(4)
	v_mfma_f32_32x32x16_bf16 v[66:81], v[118:121], v[82:85], 0
	v_add_u32_e32 v186, s9, v173
	v_or_b32_e32 v202, 2, v186
	v_or_b32_e32 v200, 3, v186
	v_add_u32_e32 v192, 8, v186
	v_add_u32_e32 v201, 9, v186
	v_add_u32_e32 v193, 10, v186
	v_add_u32_e32 v191, 11, v186
	v_mfma_f32_32x32x16_bf16 v[66:81], v[122:125], v[86:89], v[66:81]
	v_add_u32_e32 v190, 16, v186
	v_add_u32_e32 v189, 17, v186
	v_add_u32_e32 v188, 18, v186
	v_add_u32_e32 v187, 19, v186
	s_and_b64 vcc, exec, s[56:57]
	v_cmp_le_i32_e64 s[10:11], v186, v172
	v_cmp_lt_i32_e64 s[8:9], v186, v172
	v_mfma_f32_32x32x16_bf16 v[66:81], v[126:129], v[90:93], v[66:81]
	v_cmp_le_i32_e64 s[30:31], v202, v172
	v_cmp_le_i32_e64 s[28:29], v200, v172
	v_cmp_le_i32_e64 s[26:27], v192, v172
	v_cmp_le_i32_e64 s[22:23], v201, v172
	v_cmp_le_i32_e64 s[18:19], v193, v172
	v_cmp_le_i32_e64 s[14:15], v191, v172
	v_cmp_le_i32_e64 s[12:13], v190, v172
	v_mfma_f32_32x32x16_bf16 v[66:81], v[114:117], v[94:97], v[66:81]
	v_cmp_le_i32_e64 s[24:25], v189, v172
	v_cmp_le_i32_e64 s[20:21], v188, v172
	v_cmp_le_i32_e64 s[16:17], v187, v172
	v_mfma_f32_32x32x16_bf16 v[222:237], v[118:121], v[98:101], 0
	v_mfma_f32_32x32x16_bf16 v[222:237], v[122:125], v[102:105], v[222:237]
	v_mfma_f32_32x32x16_bf16 v[222:237], v[126:129], v[106:109], v[222:237]
	v_mfma_f32_32x32x16_bf16 v[222:237], v[114:117], v[110:113], v[222:237]
	s_lshl_b32 s98, s90, 5
	s_add_i32 s98, s98, s91
	s_lshl_b32 s74, s98, 7
	v_lshl_add_u64 v[220:221], v[240:241], 0, s[74:75]
	global_load_dwordx4 v[118:121], v[220:221], off
	global_load_dwordx4 v[122:125], v[220:221], off offset:1024
	global_load_dwordx4 v[126:129], v[220:221], off offset:2048
	global_load_dwordx4 v[114:117], v[220:221], off offset:3072
	s_cbranch_vccnz .LBB0_632
	s_and_b64 vcc, s[6:7], s[10:11]
	s_nop 6
	v_cndmask_b32_e32 v66, v248, v66, vcc
	s_and_b64 vcc, s[6:7], s[8:9]
	v_cndmask_b32_e32 v67, v248, v67, vcc
	s_and_b64 vcc, s[6:7], s[30:31]
	v_cndmask_b32_e32 v68, v248, v68, vcc
	s_and_b64 vcc, s[6:7], s[28:29]
	v_cndmask_b32_e32 v69, v248, v69, vcc
	s_and_b64 vcc, s[6:7], s[26:27]
	v_cndmask_b32_e32 v70, v248, v70, vcc
	s_and_b64 vcc, s[6:7], s[22:23]
	v_cndmask_b32_e32 v71, v248, v71, vcc
	s_and_b64 vcc, s[6:7], s[18:19]
	v_cndmask_b32_e32 v72, v248, v72, vcc
	s_and_b64 vcc, s[6:7], s[14:15]
	v_cndmask_b32_e32 v73, v248, v73, vcc
	s_and_b64 vcc, s[6:7], s[12:13]
	v_cndmask_b32_e32 v74, v248, v74, vcc
	s_and_b64 vcc, s[6:7], s[24:25]
	v_cndmask_b32_e32 v75, v248, v75, vcc
	s_and_b64 vcc, s[6:7], s[20:21]
	v_cndmask_b32_e32 v76, v248, v76, vcc
	s_and_b64 vcc, s[6:7], s[16:17]
	v_add_u32_e32 v0, 24, v186
	v_cndmask_b32_e32 v77, v248, v77, vcc
	v_cmp_le_i32_e32 vcc, v0, v172
	s_and_b64 vcc, s[6:7], vcc
	v_add_u32_e32 v0, 25, v186
	v_cndmask_b32_e32 v78, v248, v78, vcc
	v_cmp_le_i32_e32 vcc, v0, v172
	s_and_b64 vcc, s[6:7], vcc
	v_add_u32_e32 v0, 26, v186
	v_cndmask_b32_e32 v79, v248, v79, vcc
	v_cmp_le_i32_e32 vcc, v0, v172
	s_and_b64 vcc, s[6:7], vcc
	v_add_u32_e32 v0, 27, v186
	v_cndmask_b32_e32 v80, v248, v80, vcc
	v_cmp_le_i32_e32 vcc, v0, v172
	s_and_b64 vcc, s[6:7], vcc
	s_nop 0
	v_cndmask_b32_e32 v81, v248, v81, vcc

.LBB0_635:
	v_cndmask_b32_e64 v238, -v248, v0, s[6:7]
	v_fma_f32 v66, v66, s66, -v238
	v_exp_f32_e32 v203, v66
	v_fma_f32 v66, v67, s66, -v238
	v_exp_f32_e32 v204, v66
	v_fma_f32 v66, v68, s66, -v238
	v_exp_f32_e32 v205, v66
	v_fma_f32 v66, v69, s66, -v238
	v_exp_f32_e32 v206, v66
	v_fma_f32 v66, v70, s66, -v238
	v_exp_f32_e32 v207, v66
	v_fma_f32 v66, v71, s66, -v238
	v_exp_f32_e32 v208, v66
	v_fma_f32 v66, v72, s66, -v238
	v_exp_f32_e32 v209, v66
	v_fma_f32 v66, v73, s66, -v238
	v_exp_f32_e32 v210, v66
	v_fma_f32 v66, v74, s66, -v238
	v_exp_f32_e32 v211, v66
	v_fma_f32 v66, v75, s66, -v238
	v_exp_f32_e32 v212, v66
	v_fma_f32 v66, v76, s66, -v238
	v_exp_f32_e32 v213, v66
	v_fma_f32 v66, v77, s66, -v238
	v_exp_f32_e32 v214, v66
	v_fma_f32 v66, v78, s66, -v238
	v_exp_f32_e32 v215, v66
	v_fma_f32 v66, v79, s66, -v238
	v_exp_f32_e32 v216, v66
	v_fma_f32 v66, v80, s66, -v238
	v_exp_f32_e32 v217, v66
	v_fma_f32 v66, v81, s66, -v238
	v_exp_f32_e32 v218, v66
	v_cvt_pk_bf16_f32 v66, v203, v204
	v_cvt_pk_bf16_f32 v67, v205, v206
	v_cvt_pk_bf16_f32 v68, v207, v208
	v_cvt_pk_bf16_f32 v69, v209, v210
	v_cvt_pk_bf16_f32 v70, v211, v212
	v_cvt_pk_bf16_f32 v71, v213, v214
	v_cvt_pk_bf16_f32 v72, v215, v216
	v_cvt_pk_bf16_f32 v73, v217, v218
	s_xor_b64 s[6:7], s[56:57], -1
	s_andn2_b64 vcc, exec, s[6:7]
	s_cbranch_vccnz .LBB0_637
	v_cmp_le_i32_e32 vcc, v186, v174
	s_and_b64 vcc, s[4:5], vcc
	s_nop 4
	v_cndmask_b32_e32 v222, v248, v222, vcc
	v_cmp_lt_i32_e32 vcc, v186, v174
	s_and_b64 vcc, s[4:5], vcc
	s_nop 0
	v_cndmask_b32_e32 v223, v248, v223, vcc
	v_cmp_le_i32_e32 vcc, v186, v175
	s_and_b64 vcc, s[4:5], vcc
	s_nop 0
	v_cndmask_b32_e32 v224, v248, v224, vcc
	v_cmp_le_i32_e32 vcc, v186, v184
	s_and_b64 vcc, s[4:5], vcc
	s_nop 0
	v_cndmask_b32_e32 v225, v248, v225, vcc
	v_cmp_le_i32_e32 vcc, v186, v172
	s_and_b64 vcc, s[4:5], vcc
	s_nop 0
	v_cndmask_b32_e32 v226, v248, v226, vcc
	v_cmp_lt_i32_e32 vcc, v186, v172
	s_and_b64 vcc, s[4:5], vcc
	s_nop 0
	v_cndmask_b32_e32 v227, v248, v227, vcc
	v_cmp_le_i32_e32 vcc, v202, v172
	s_and_b64 vcc, s[4:5], vcc
	s_nop 0
	v_cndmask_b32_e32 v228, v248, v228, vcc
	v_cmp_le_i32_e32 vcc, v200, v172
	s_and_b64 vcc, s[4:5], vcc
	s_nop 0
	v_cndmask_b32_e32 v229, v248, v229, vcc
	v_cmp_le_i32_e32 vcc, v192, v172
	s_and_b64 vcc, s[4:5], vcc
	s_nop 0
	v_cndmask_b32_e32 v230, v248, v230, vcc
	v_cmp_le_i32_e32 vcc, v201, v172
	s_and_b64 vcc, s[4:5], vcc
	s_nop 0
	v_cndmask_b32_e32 v231, v248, v231, vcc
	v_cmp_le_i32_e32 vcc, v193, v172
	s_and_b64 vcc, s[4:5], vcc
	s_nop 0
	v_cndmask_b32_e32 v232, v248, v232, vcc
	v_cmp_le_i32_e32 vcc, v191, v172
	s_and_b64 vcc, s[4:5], vcc
	s_nop 0
	v_cndmask_b32_e32 v233, v248, v233, vcc
	v_cmp_le_i32_e32 vcc, v190, v172
	s_and_b64 vcc, s[4:5], vcc
	s_nop 0
	v_cndmask_b32_e32 v234, v248, v234, vcc
	v_cmp_le_i32_e32 vcc, v189, v172
	s_and_b64 vcc, s[4:5], vcc
	s_nop 0
	v_cndmask_b32_e32 v235, v248, v235, vcc
	v_cmp_le_i32_e32 vcc, v188, v172
	s_and_b64 vcc, s[4:5], vcc
	s_nop 0
	v_cndmask_b32_e32 v236, v248, v236, vcc
	v_cmp_le_i32_e32 vcc, v187, v172
	s_and_b64 vcc, s[4:5], vcc
	s_nop 0
	v_cndmask_b32_e32 v237, v248, v237, vcc
.LBB0_637:
	s_nop 6
	v_max_f32_e32 v186, v223, v223
	v_max_f32_e32 v187, v222, v222
	v_max_f32_e32 v186, v187, v186
	v_max3_f32 v186, v186, v224, v225
	v_max3_f32 v186, v186, v226, v227
	v_max3_f32 v186, v186, v228, v229
	v_max3_f32 v186, v186, v230, v231
	v_max3_f32 v186, v186, v232, v233
	v_max3_f32 v186, v186, v234, v235
	v_max3_f32 v186, v186, v236, v237
	v_cndmask_b32_e64 v186, v248, v186, s[4:5]
	v_mov_b32_e32 v187, v186
	s_nop 1
	v_permlane32_swap_b32_e32 v186, v187
	v_max_f32_e32 v187, v187, v187
	v_max_f32_e32 v186, v186, v186
	v_max_f32_e32 v186, v186, v187
	v_mul_f32_e32 v186, 0x3e38aa3b, v186
	v_max_f32_e32 v187, v185, v185
	v_max_f32_e32 v186, v187, v186
	v_sub_f32_e32 v187, v186, v185
	v_cmp_lt_f32_e32 vcc, s67, v187
	s_cbranch_vccz .LBB0_639
	v_sub_f32_e32 v185, v185, v186
	v_exp_f32_e32 v188, v185
	s_nop 0
	v_mul_f32_e32 v150, v150, v188
	v_pk_mul_f32 v[32:33], v[32:33], v[188:189] op_sel_hi:[1,0]
	v_pk_mul_f32 v[30:31], v[30:31], v[188:189] op_sel_hi:[1,0]
	v_pk_mul_f32 v[28:29], v[28:29], v[188:189] op_sel_hi:[1,0]
	v_pk_mul_f32 v[26:27], v[26:27], v[188:189] op_sel_hi:[1,0]
	v_pk_mul_f32 v[24:25], v[24:25], v[188:189] op_sel_hi:[1,0]
	v_pk_mul_f32 v[22:23], v[22:23], v[188:189] op_sel_hi:[1,0]
	v_pk_mul_f32 v[20:21], v[20:21], v[188:189] op_sel_hi:[1,0]
	v_pk_mul_f32 v[18:19], v[18:19], v[188:189] op_sel_hi:[1,0]
	v_pk_mul_f32 v[16:17], v[16:17], v[188:189] op_sel_hi:[1,0]
	v_pk_mul_f32 v[14:15], v[14:15], v[188:189] op_sel_hi:[1,0]
	v_pk_mul_f32 v[12:13], v[12:13], v[188:189] op_sel_hi:[1,0]
	v_pk_mul_f32 v[10:11], v[10:11], v[188:189] op_sel_hi:[1,0]
	v_pk_mul_f32 v[8:9], v[8:9], v[188:189] op_sel_hi:[1,0]
	v_pk_mul_f32 v[6:7], v[6:7], v[188:189] op_sel_hi:[1,0]
	v_pk_mul_f32 v[4:5], v[4:5], v[188:189] op_sel_hi:[1,0]
	v_pk_mul_f32 v[2:3], v[2:3], v[188:189] op_sel_hi:[1,0]
	s_branch .LBB0_640

.LBB0_640:
	v_cndmask_b32_e64 v239, -v248, v186, s[4:5]
	v_add_f32_e32 v185, 0, v203
	v_add_f32_e32 v185, v204, v185
	v_add_f32_e32 v185, v205, v185
	v_add_f32_e32 v185, v206, v185
	v_add_f32_e32 v185, v207, v185
	v_add_f32_e32 v185, v208, v185
	v_add_f32_e32 v185, v209, v185
	v_add_f32_e32 v185, v210, v185
	v_add_f32_e32 v185, v211, v185
	v_add_f32_e32 v185, v212, v185
	v_add_f32_e32 v185, v213, v185
	v_add_f32_e32 v185, v214, v185
	v_fma_f32 v222, v222, s66, -v239
	v_add_f32_e32 v185, v215, v185
	v_exp_f32_e32 v222, v222
	v_fma_f32 v223, v223, s66, -v239
	v_add_f32_e32 v185, v216, v185
	v_exp_f32_e32 v223, v223
	v_fma_f32 v224, v224, s66, -v239
	v_add_f32_e32 v185, v217, v185
	v_exp_f32_e32 v224, v224
	v_fma_f32 v225, v225, s66, -v239
	v_fma_f32 v226, v226, s66, -v239
	v_fma_f32 v227, v227, s66, -v239
	v_fma_f32 v228, v228, s66, -v239
	v_fma_f32 v229, v229, s66, -v239
	v_add_f32_e32 v185, v218, v185
	v_exp_f32_e32 v225, v225
	v_exp_f32_e32 v226, v226
	v_exp_f32_e32 v227, v227
	v_exp_f32_e32 v228, v228
	v_exp_f32_e32 v229, v229
	v_add_f32_e32 v151, v151, v185
	v_add_f32_e32 v185, 0, v222
	v_add_f32_e32 v185, v223, v185
	v_add_f32_e32 v185, v224, v185
	v_add_f32_e32 v185, v225, v185
	v_cvt_pk_bf16_f32 v222, v222, v223
	v_cvt_pk_bf16_f32 v223, v224, v225
	v_cvt_pk_bf16_f32 v224, v226, v227
	v_cvt_pk_bf16_f32 v225, v228, v229
	v_fma_f32 v230, v230, s66, -v239
	v_fma_f32 v231, v231, s66, -v239
	s_waitcnt vmcnt(4) lgkmcnt(0)
	v_mfma_f32_32x32x16_bf16 v[50:65], v[142:145], v[66:69], v[50:65]
	v_mfma_f32_32x32x16_bf16 v[34:49], v[134:137], v[66:69], v[34:49]
	v_mfma_f32_32x32x16_bf16 v[50:65], v[138:141], v[70:73], v[50:65]
	v_mfma_f32_32x32x16_bf16 v[34:49], v[130:133], v[70:73], v[34:49]
	v_mfma_f32_32x32x16_bf16 v[18:33], v[142:145], v[222:225], v[18:33]
	v_fma_f32 v232, v232, s66, -v239
	v_fma_f32 v233, v233, s66, -v239
	v_fma_f32 v234, v234, s66, -v239
	v_fma_f32 v235, v235, s66, -v239
	v_fma_f32 v236, v236, s66, -v239
	v_fma_f32 v237, v237, s66, -v239
	v_add_f32_e32 v185, v226, v185
	v_mfma_f32_32x32x16_bf16 v[2:17], v[134:137], v[222:225], v[2:17]
	v_exp_f32_e32 v230, v230
	v_exp_f32_e32 v231, v231
	v_exp_f32_e32 v232, v232
	v_exp_f32_e32 v233, v233
	v_exp_f32_e32 v234, v234
	v_exp_f32_e32 v235, v235
	v_exp_f32_e32 v236, v236
	v_exp_f32_e32 v237, v237
	v_add_f32_e32 v185, v227, v185
	v_add_f32_e32 v185, v228, v185
	v_add_f32_e32 v185, v229, v185
	v_add_f32_e32 v185, v230, v185
	v_cvt_pk_bf16_f32 v226, v230, v231
	v_cvt_pk_bf16_f32 v227, v232, v233
	v_cvt_pk_bf16_f32 v228, v234, v235
	v_cvt_pk_bf16_f32 v229, v236, v237
	v_add_f32_e32 v185, v231, v185
	v_add_f32_e32 v185, v232, v185
	v_mfma_f32_32x32x16_bf16 v[18:33], v[138:141], v[226:229], v[18:33]
	v_add_f32_e32 v185, v233, v185
	v_add_f32_e32 v185, v234, v185
	v_add_f32_e32 v185, v235, v185
	v_add_f32_e32 v185, v236, v185
	s_xor_b64 s[4:5], s[96:97], -1
	v_add_f32_e32 v185, v237, v185
	v_add_f32_e32 v150, v150, v185
	v_mfma_f32_32x32x16_bf16 v[2:17], v[130:133], v[226:229], v[2:17]
	s_and_b64 vcc, exec, s[4:5]
	s_cbranch_vccnz .LBB0_642
	s_lshl_b32 s74, s98, 7
	v_lshl_add_u64 v[220:221], v[182:183], 0, s[74:75]
	global_load_dwordx4 v[142:145], v[220:221], off
	global_load_dwordx4 v[138:141], v[220:221], off offset:2048
	global_load_dwordx4 v[134:137], v[220:221], off offset:1024
	global_load_dwordx4 v[130:133], v[220:221], off offset:3072
	s_mov_b32 s8, s90
	s_mov_b32 s4, s83
	v_mov_b32_e32 v203, v0
	v_mov_b32_e32 v185, v186
	s_branch .LBB0_626
